# lever 7: GEMM accumulators zeroed with 64 v_mov_b64 instead of 128 v_mov_b32 per unit
# speedup vs baseline: 1.0076x; 1.0076x over previous
; template <class Epi>
; DI void gemm_phase(PG8_LAS unsigned char* lds, const Gemm g, const StaticOrder& S, const Epi& E) {
;     ...
;     const bool has_next = S.next(ui + 1, nxt);
;     const char* nA = has_next ? (const char*)g.A + (size_t)nxt.pm * tstepA : cA; const char* nB = has_next ? (const char*)g.Bt + (size_t)nxt.pn * tstepB : cB;
;     ...
; #pragma unroll
;     for (int a = 0; a < 2; ++a)
; #pragma unroll
;       for (int b = 0; b < 2; ++b)
; #pragma unroll
;         for (int m = 0; m < 4; ++m)
; #pragma unroll
;           for (int n = 0; n < 2; ++n) acc[a][b][m][n] = (f32x4){0.f, 0.f, 0.f, 0.f};
.LBB0_51:
	v_mov_b64_e32 v[2:3], 0x580
	s_ashr_i32 s51, s50, 31
	v_cmp_lt_i64_e32 vcc, s[52:53], v[2:3]
	s_lshl_b64 s[52:53], s[50:51], 19
	s_add_u32 s52, s22, s52
	s_addc_u32 s53, s23, s53
	s_and_b64 s[54:55], vcc, exec
	s_cselect_b32 s51, s53, s57
	s_cselect_b32 s72, s52, s56
	s_ashr_i32 s31, s30, 31
	s_lshl_b64 s[54:55], s[30:31], 19
	v_readlane_b32 s60, v252, 11
	v_readlane_b32 s61, v252, 12
	s_add_u32 s54, s60, s54
	s_addc_u32 s55, s61, s55
	s_and_b64 s[60:61], vcc, exec
	s_cselect_b32 s31, s55, s59
	s_cselect_b32 s73, s54, s58
	s_add_u32 s56, s56, 0x40080
	s_addc_u32 s57, s57, 0
	s_add_u32 s74, s58, 0x100
	v_mov_b32_e32 v2, 0
	s_addc_u32 s75, s59, 0
	s_mov_b32 s76, -2
	v_mov_b64_e32 v[2:3], 0
	v_mov_b64_e32 v[4:5], 0
	v_mov_b64_e32 v[6:7], 0
	v_mov_b64_e32 v[8:9], 0
	v_mov_b64_e32 v[10:11], 0
	v_mov_b64_e32 v[12:13], 0
	v_mov_b64_e32 v[14:15], 0
	v_mov_b64_e32 v[16:17], 0
	v_mov_b64_e32 v[18:19], 0
	v_mov_b64_e32 v[20:21], 0
	v_mov_b64_e32 v[22:23], 0
	v_mov_b64_e32 v[24:25], 0
	v_mov_b64_e32 v[26:27], 0
	v_mov_b64_e32 v[28:29], 0
	v_mov_b64_e32 v[30:31], 0
	v_mov_b64_e32 v[32:33], 0
	v_mov_b64_e32 v[34:35], 0
	v_mov_b64_e32 v[36:37], 0
	v_mov_b64_e32 v[38:39], 0
	v_mov_b64_e32 v[40:41], 0
	v_mov_b64_e32 v[42:43], 0
	v_mov_b64_e32 v[44:45], 0
	v_mov_b64_e32 v[46:47], 0
	v_mov_b64_e32 v[48:49], 0
	v_mov_b64_e32 v[50:51], 0
	v_mov_b64_e32 v[52:53], 0
	v_mov_b64_e32 v[54:55], 0
	v_mov_b64_e32 v[56:57], 0
	v_mov_b64_e32 v[58:59], 0
	v_mov_b64_e32 v[60:61], 0
	v_mov_b64_e32 v[62:63], 0
	v_mov_b64_e32 v[64:65], 0
	v_mov_b64_e32 v[66:67], 0
	v_mov_b64_e32 v[68:69], 0
	v_mov_b64_e32 v[70:71], 0
	v_mov_b64_e32 v[72:73], 0
	v_mov_b64_e32 v[74:75], 0
	v_mov_b64_e32 v[76:77], 0
	v_mov_b64_e32 v[78:79], 0
	v_mov_b64_e32 v[80:81], 0
	v_mov_b64_e32 v[82:83], 0
	v_mov_b64_e32 v[84:85], 0
	v_mov_b64_e32 v[86:87], 0
	v_mov_b64_e32 v[88:89], 0
	v_mov_b64_e32 v[90:91], 0
	v_mov_b64_e32 v[92:93], 0
	v_mov_b64_e32 v[94:95], 0
	v_mov_b64_e32 v[96:97], 0
	v_mov_b64_e32 v[98:99], 0
	v_mov_b64_e32 v[100:101], 0
	v_mov_b64_e32 v[102:103], 0
	v_mov_b64_e32 v[104:105], 0
	v_mov_b64_e32 v[106:107], 0
	v_mov_b64_e32 v[108:109], 0
	v_mov_b64_e32 v[110:111], 0
	v_mov_b64_e32 v[112:113], 0
	v_mov_b64_e32 v[114:115], 0
	v_mov_b64_e32 v[116:117], 0
	v_mov_b64_e32 v[118:119], 0
	v_mov_b64_e32 v[120:121], 0
	v_mov_b64_e32 v[122:123], 0
	v_mov_b64_e32 v[124:125], 0
	v_mov_b64_e32 v[126:127], 0
	v_mov_b64_e32 v[128:129], 0

; template <class Epi>
; DI void gemm_phase(PG8_LAS unsigned char* lds, const Gemm g, const StaticOrder& S, const Epi& E) {
;     ...
;     const bool has_next = S.next(ui + 1, nxt);
;     const char* nA = has_next ? (const char*)g.A + (size_t)nxt.pm * tstepA : cA; const char* nB = has_next ? (const char*)g.Bt + (size_t)nxt.pn * tstepB : cB;
;     for (int t = 0; t < nt; t += 2) {
;       const bool last = (t == nt - 2);
;       const char* a1 = cA + (size_t)(t + 1) * kstep;
;       const char* a2 = last ? nA : cA + (size_t)(t + 2) * kstep; const char* b2 = last ? nB : cB + (size_t)(t + 2) * kstep;
;     ...
; #pragma unroll
;     for (int a = 0; a < 2; ++a)
; #pragma unroll
;       for (int b = 0; b < 2; ++b)
; #pragma unroll
;         for (int m = 0; m < 4; ++m)
; #pragma unroll
;           for (int n = 0; n < 2; ++n) acc[a][b][m][n] = (f32x4){0.f, 0.f, 0.f, 0.f};
.LBB0_834:
	s_add_u32 s44, s58, 0x80
	s_addc_u32 s45, s59, 0
	s_add_u32 s79, s56, 0x100
	v_mov_b32_e32 v2, 0
	s_addc_u32 s80, s57, 0
	s_mov_b32 s56, 0
	v_mov_b64_e32 v[2:3], 0
	v_mov_b64_e32 v[4:5], 0
	v_mov_b64_e32 v[6:7], 0
	v_mov_b64_e32 v[8:9], 0
	v_mov_b64_e32 v[10:11], 0
	v_mov_b64_e32 v[12:13], 0
	v_mov_b64_e32 v[14:15], 0
	v_mov_b64_e32 v[16:17], 0
	v_mov_b64_e32 v[18:19], 0
	v_mov_b64_e32 v[20:21], 0
	v_mov_b64_e32 v[22:23], 0
	v_mov_b64_e32 v[24:25], 0
	v_mov_b64_e32 v[26:27], 0
	v_mov_b64_e32 v[28:29], 0
	v_mov_b64_e32 v[30:31], 0
	v_mov_b64_e32 v[32:33], 0
	v_mov_b64_e32 v[34:35], 0
	v_mov_b64_e32 v[36:37], 0
	v_mov_b64_e32 v[38:39], 0
	v_mov_b64_e32 v[40:41], 0
	v_mov_b64_e32 v[42:43], 0
	v_mov_b64_e32 v[44:45], 0
	v_mov_b64_e32 v[46:47], 0
	v_mov_b64_e32 v[48:49], 0
	v_mov_b64_e32 v[50:51], 0
	v_mov_b64_e32 v[52:53], 0
	v_mov_b64_e32 v[54:55], 0
	v_mov_b64_e32 v[56:57], 0
	v_mov_b64_e32 v[58:59], 0
	v_mov_b64_e32 v[60:61], 0
	v_mov_b64_e32 v[62:63], 0
	v_mov_b64_e32 v[64:65], 0
	v_mov_b64_e32 v[66:67], 0
	v_mov_b64_e32 v[68:69], 0
	v_mov_b64_e32 v[70:71], 0
	v_mov_b64_e32 v[72:73], 0
	v_mov_b64_e32 v[74:75], 0
	v_mov_b64_e32 v[76:77], 0
	v_mov_b64_e32 v[78:79], 0
	v_mov_b64_e32 v[80:81], 0
	v_mov_b64_e32 v[82:83], 0
	v_mov_b64_e32 v[84:85], 0
	v_mov_b64_e32 v[86:87], 0
	v_mov_b64_e32 v[88:89], 0
	v_mov_b64_e32 v[90:91], 0
	v_mov_b64_e32 v[92:93], 0
	v_mov_b64_e32 v[94:95], 0
	v_mov_b64_e32 v[96:97], 0
	v_mov_b64_e32 v[98:99], 0
	v_mov_b64_e32 v[100:101], 0
	v_mov_b64_e32 v[102:103], 0
	v_mov_b64_e32 v[104:105], 0
	v_mov_b64_e32 v[106:107], 0
	v_mov_b64_e32 v[108:109], 0
	v_mov_b64_e32 v[110:111], 0
	v_mov_b64_e32 v[112:113], 0
	v_mov_b64_e32 v[114:115], 0
	v_mov_b64_e32 v[116:117], 0
	v_mov_b64_e32 v[118:119], 0
	v_mov_b64_e32 v[120:121], 0
	v_mov_b64_e32 v[122:123], 0
	v_mov_b64_e32 v[124:125], 0
	v_mov_b64_e32 v[126:127], 0
	v_mov_b64_e32 v[128:129], 0

; template <class Epi>
; DI void gemm_phase(PG8_LAS unsigned char* lds, const Gemm g, const StaticOrder& S, const Epi& E) {
;     ...
;     const bool has_next = S.next(ui + 1, nxt);
;     const char* nA = has_next ? (const char*)g.A + (size_t)nxt.pm * tstepA : cA; const char* nB = has_next ? (const char*)g.Bt + (size_t)nxt.pn * tstepB : cB;
;     for (int t = 0; t < nt; t += 2) {
;       const bool last = (t == nt - 2);
;       const char* a1 = cA + (size_t)(t + 1) * kstep;
;       const char* a2 = last ? nA : cA + (size_t)(t + 2) * kstep; const char* b2 = last ? nB : cB + (size_t)(t + 2) * kstep;
;     ...
; #pragma unroll
;     for (int a = 0; a < 2; ++a)
; #pragma unroll
;       for (int b = 0; b < 2; ++b)
; #pragma unroll
;         for (int m = 0; m < 4; ++m)
; #pragma unroll
;           for (int n = 0; n < 2; ++n) acc[a][b][m][n] = (f32x4){0.f, 0.f, 0.f, 0.f};
.LBB0_1174:
	s_ashr_i32 s47, s46, 31
	v_cmp_lt_i64_e32 vcc, s[48:49], v[136:137]
	s_lshl_b64 s[48:49], s[46:47], 19
	s_add_u32 s48, s22, s48
	s_addc_u32 s49, s23, s49
	s_and_b64 s[50:51], vcc, exec
	s_cselect_b32 s47, s49, s31
	s_cselect_b32 s66, s48, s30
	s_ashr_i32 s45, s44, 31
	v_readlane_b32 s4, v253, 16
	s_lshl_b64 s[50:51], s[44:45], 19
	v_readlane_b32 s14, v253, 26
	v_readlane_b32 s15, v253, 27
	s_add_u32 s50, s14, s50
	s_addc_u32 s51, s15, s51
	s_and_b64 s[54:55], vcc, exec
	s_cselect_b32 s45, s51, s53
	s_cselect_b32 s67, s50, s52
	s_add_u32 s30, s30, 0x40080
	s_addc_u32 s31, s31, 0
	s_add_u32 s68, s52, 0x100
	v_mov_b32_e32 v18, 0
	s_addc_u32 s69, s53, 0
	s_mov_b32 s70, -2
	v_mov_b64_e32 v[2:3], 0
	v_mov_b64_e32 v[4:5], 0
	v_mov_b64_e32 v[6:7], 0
	v_mov_b64_e32 v[8:9], 0
	v_mov_b64_e32 v[10:11], 0
	v_mov_b64_e32 v[12:13], 0
	v_mov_b64_e32 v[14:15], 0
	v_mov_b64_e32 v[16:17], 0
	v_mov_b64_e32 v[18:19], 0
	v_mov_b64_e32 v[20:21], 0
	v_mov_b64_e32 v[22:23], 0
	v_mov_b64_e32 v[24:25], 0
	v_mov_b64_e32 v[26:27], 0
	v_mov_b64_e32 v[28:29], 0
	v_mov_b64_e32 v[30:31], 0
	v_mov_b64_e32 v[32:33], 0
	v_mov_b64_e32 v[34:35], 0
	v_mov_b64_e32 v[36:37], 0
	v_mov_b64_e32 v[38:39], 0
	v_mov_b64_e32 v[40:41], 0
	v_mov_b64_e32 v[42:43], 0
	v_mov_b64_e32 v[44:45], 0
	v_mov_b64_e32 v[46:47], 0
	v_mov_b64_e32 v[48:49], 0
	v_mov_b64_e32 v[50:51], 0
	v_mov_b64_e32 v[52:53], 0
	v_mov_b64_e32 v[54:55], 0
	v_mov_b64_e32 v[56:57], 0
	v_mov_b64_e32 v[58:59], 0
	v_mov_b64_e32 v[60:61], 0
	v_mov_b64_e32 v[62:63], 0
	v_mov_b64_e32 v[64:65], 0
	v_mov_b64_e32 v[66:67], 0
	v_mov_b64_e32 v[68:69], 0
	v_mov_b64_e32 v[70:71], 0
	v_mov_b64_e32 v[72:73], 0
	v_mov_b64_e32 v[74:75], 0
	v_mov_b64_e32 v[76:77], 0
	v_mov_b64_e32 v[78:79], 0
	v_mov_b64_e32 v[80:81], 0
	v_mov_b64_e32 v[82:83], 0
	v_mov_b64_e32 v[84:85], 0
	v_mov_b64_e32 v[86:87], 0
	v_mov_b64_e32 v[88:89], 0
	v_mov_b64_e32 v[90:91], 0
	v_mov_b64_e32 v[92:93], 0
	v_mov_b64_e32 v[94:95], 0
	v_mov_b64_e32 v[96:97], 0
	v_mov_b64_e32 v[98:99], 0
	v_mov_b64_e32 v[100:101], 0
	v_mov_b64_e32 v[102:103], 0
	v_mov_b64_e32 v[104:105], 0
	v_mov_b64_e32 v[106:107], 0
	v_mov_b64_e32 v[108:109], 0
	v_mov_b64_e32 v[110:111], 0
	v_mov_b64_e32 v[112:113], 0
	v_mov_b64_e32 v[114:115], 0
	v_mov_b64_e32 v[116:117], 0
	v_mov_b64_e32 v[118:119], 0
	v_mov_b64_e32 v[120:121], 0
	v_mov_b64_e32 v[122:123], 0
	v_mov_b64_e32 v[124:125], 0
	v_mov_b64_e32 v[126:127], 0
	v_mov_b64_e32 v[128:129], 0
	v_readlane_b32 s5, v253, 17
	v_readlane_b32 s6, v253, 18
	v_readlane_b32 s7, v253, 19
	v_readlane_b32 s8, v253, 20
	v_readlane_b32 s9, v253, 21
	v_readlane_b32 s10, v253, 22
	v_readlane_b32 s11, v253, 23
	v_readlane_b32 s12, v253, 24
	v_readlane_b32 s13, v253, 25
	v_readlane_b32 s16, v253, 28
	v_readlane_b32 s17, v253, 29
	v_readlane_b32 s18, v253, 30
	v_readlane_b32 s19, v253, 31

; template <class Epi>
; DI void gemm_phase(PG8_LAS unsigned char* lds, const Gemm g, const StaticOrder& S, const Epi& E) {
;     ...
;     const bool has_next = S.next(ui + 1, nxt);
;     const char* nA = has_next ? (const char*)g.A + (size_t)nxt.pm * tstepA : cA; const char* nB = has_next ? (const char*)g.Bt + (size_t)nxt.pn * tstepB : cB;
;     for (int t = 0; t < nt; t += 2) {
;       const bool last = (t == nt - 2);
;       const char* a1 = cA + (size_t)(t + 1) * kstep;
;       const char* a2 = last ? nA : cA + (size_t)(t + 2) * kstep; const char* b2 = last ? nB : cB + (size_t)(t + 2) * kstep;
;     ...
; #pragma unroll
;     for (int a = 0; a < 2; ++a)
; #pragma unroll
;       for (int b = 0; b < 2; ++b)
; #pragma unroll
;         for (int m = 0; m < 4; ++m)
; #pragma unroll
;           for (int n = 0; n < 2; ++n) acc[a][b][m][n] = (f32x4){0.f, 0.f, 0.f, 0.f};
.LBB0_1196:
	s_ashr_i32 s43, s42, 31
	v_cmp_lt_i64_e32 vcc, s[44:45], v[140:141]
	s_lshl_b64 s[44:45], s[42:43], 19
	s_add_u32 s44, s22, s44
	s_addc_u32 s45, s23, s45
	s_and_b64 s[46:47], vcc, exec
	s_cselect_b32 s43, s45, s49
	s_cselect_b32 s63, s44, s48
	s_ashr_i32 s31, s30, 31
	v_readlane_b32 s4, v253, 16
	s_lshl_b64 s[46:47], s[30:31], 19
	v_readlane_b32 s14, v253, 26
	v_readlane_b32 s15, v253, 27
	s_add_u32 s46, s14, s46
	s_addc_u32 s47, s15, s47
	s_and_b64 s[52:53], vcc, exec
	s_cselect_b32 s31, s47, s51
	s_cselect_b32 s64, s46, s50
	s_add_u32 s48, s48, 0x40080
	s_addc_u32 s49, s49, 0
	s_add_u32 s65, s50, 0x100
	v_mov_b32_e32 v2, 0
	s_addc_u32 s66, s51, 0
	s_mov_b32 s67, -2
	v_mov_b64_e32 v[2:3], 0
	v_mov_b64_e32 v[4:5], 0
	v_mov_b64_e32 v[6:7], 0
	v_mov_b64_e32 v[8:9], 0
	v_mov_b64_e32 v[10:11], 0
	v_mov_b64_e32 v[12:13], 0
	v_mov_b64_e32 v[14:15], 0
	v_mov_b64_e32 v[16:17], 0
	v_mov_b64_e32 v[18:19], 0
	v_mov_b64_e32 v[20:21], 0
	v_mov_b64_e32 v[22:23], 0
	v_mov_b64_e32 v[24:25], 0
	v_mov_b64_e32 v[26:27], 0
	v_mov_b64_e32 v[28:29], 0
	v_mov_b64_e32 v[30:31], 0
	v_mov_b64_e32 v[32:33], 0
	v_mov_b64_e32 v[34:35], 0
	v_mov_b64_e32 v[36:37], 0
	v_mov_b64_e32 v[38:39], 0
	v_mov_b64_e32 v[40:41], 0
	v_mov_b64_e32 v[42:43], 0
	v_mov_b64_e32 v[44:45], 0
	v_mov_b64_e32 v[46:47], 0
	v_mov_b64_e32 v[48:49], 0
	v_mov_b64_e32 v[50:51], 0
	v_mov_b64_e32 v[52:53], 0
	v_mov_b64_e32 v[54:55], 0
	v_mov_b64_e32 v[56:57], 0
	v_mov_b64_e32 v[58:59], 0
	v_mov_b64_e32 v[60:61], 0
	v_mov_b64_e32 v[62:63], 0
	v_mov_b64_e32 v[64:65], 0
	v_mov_b64_e32 v[66:67], 0
	v_mov_b64_e32 v[68:69], 0
	v_mov_b64_e32 v[70:71], 0
	v_mov_b64_e32 v[72:73], 0
	v_mov_b64_e32 v[74:75], 0
	v_mov_b64_e32 v[76:77], 0
	v_mov_b64_e32 v[78:79], 0
	v_mov_b64_e32 v[80:81], 0
	v_mov_b64_e32 v[82:83], 0
	v_mov_b64_e32 v[84:85], 0
	v_mov_b64_e32 v[86:87], 0
	v_mov_b64_e32 v[88:89], 0
	v_mov_b64_e32 v[90:91], 0
	v_mov_b64_e32 v[92:93], 0
	v_mov_b64_e32 v[94:95], 0
	v_mov_b64_e32 v[96:97], 0
	v_mov_b64_e32 v[98:99], 0
	v_mov_b64_e32 v[100:101], 0
	v_mov_b64_e32 v[102:103], 0
	v_mov_b64_e32 v[104:105], 0
	v_mov_b64_e32 v[106:107], 0
	v_mov_b64_e32 v[108:109], 0
	v_mov_b64_e32 v[110:111], 0
	v_mov_b64_e32 v[112:113], 0
	v_mov_b64_e32 v[114:115], 0
	v_mov_b64_e32 v[116:117], 0
	v_mov_b64_e32 v[118:119], 0
	v_mov_b64_e32 v[120:121], 0
	v_mov_b64_e32 v[122:123], 0
	v_mov_b64_e32 v[124:125], 0
	v_mov_b64_e32 v[126:127], 0
	v_mov_b64_e32 v[128:129], 0
	v_readlane_b32 s5, v253, 17
	v_readlane_b32 s6, v253, 18
	v_readlane_b32 s7, v253, 19
	v_readlane_b32 s8, v253, 20
	v_readlane_b32 s9, v253, 21
	v_readlane_b32 s10, v253, 22
	v_readlane_b32 s11, v253, 23
	v_readlane_b32 s12, v253, 24
	v_readlane_b32 s13, v253, 25
	v_readlane_b32 s16, v253, 28
	v_readlane_b32 s17, v253, 29
	v_readlane_b32 s18, v253, 30
	v_readlane_b32 s19, v253, 31
